# gate/up GEMM: first super-phase LDS operand reads of the next unit issued at the start of the SwiGLU epilogue
# baseline (speedup 1.0000x reference)
; #define PG8_STAGE(bufoff, gbase, voff) do { _Pragma("unroll") for (int _i = 0; _i < 2; ++_i) \
;         __builtin_amdgcn_global_load_lds((const unsigned*)((const char*)(gbase) + (voff)[_i]), (PG8_LAS unsigned*)(lds + (bufoff) + ldsw + _i * 8192), 16, 0, 0); } while (0)
; #define PG8_WAIT_V(n) asm volatile("s_waitcnt vmcnt(" #n ")" ::: "memory")
; #define PG8_BAR __builtin_amdgcn_s_barrier()
;     ...
;     if constexpr (Epi::ROWSCALE) { float rr0[2][4]; row_rs8(E.ssq, cur.pm * BM + wr * 64 + fr, fq, rr0);
; #pragma unroll
;         for (int m = 0; m < 4; ++m) rrp[m] = __builtin_amdgcn_cvt_pkrtz(rr0[0][m], rr0[1][m]); }
;     const char* cA = (const char*)gA + (size_t)cur.pm * tstepA + (size_t)cur.pn * acolB; const char* cB = (const char*)gB + (size_t)cur.pn * tstepB;
;     S.a_ready(cur);
;     if constexpr (SP2) {
;         PG8_STAGE(PG8_SB(0, 0), cB, voffB); PG8_STAGE(PG8_SB(0, 1), cB + hstepB, voffB); PG8_STAGE(PG8_SA(0, 0), cA, voffA); PG8_STAGE(PG8_SA(0, 1), cA + hstepA, voffA);
;         if (wr == 1) PG8_BAR;
;         PG8_WAIT_V(2); PG8_BAR;
;         PG8_STAGE(PG8_SB(1, 0), cB + kstep, voffB); PG8_STAGE(PG8_SA(1, 0), cA + kstep, voffA); PG8_STAGE(PG8_SB(1, 1), cB + hstepB + kstep, voffB);
;         PG8_WAIT_V(6); PG8_BAR;
;     } else {
;         PG8_STAGE(PG8_SB(0, 0), cB, voffB); PG8_STAGE(PG8_SA(0, 0), cA, voffA); PG8_STAGE(PG8_SB(0, 1), cB + hstepB, voffB); PG8_STAGE(PG8_SA(0, 1), cA + hstepA, voffA);
;         if (wr == 1) PG8_BAR;
;         PG8_WAIT_V(4); PG8_BAR;
;         PG8_STAGE(PG8_SB(1, 0), cB + kstep, voffB); PG8_STAGE(PG8_SA(1, 0), cA + kstep, voffA); PG8_STAGE(PG8_SB(1, 1), cB + hstepB + kstep, voffB);
;         PG8_WAIT_V(6); PG8_BAR;
.LBB0_602:
	v_add_f32_e32 v21, v21, v22
	v_add_f32_e32 v22, v23, v24
	v_add_f32_e32 v23, v25, v26
	v_add_f32_e32 v25, v29, v30
	v_fmamk_f32 v21, v21, 0x3a800000, v1
	v_add_f32_e32 v24, v27, v28
	v_fmamk_f32 v25, v25, 0x3a800000, v1
	s_waitcnt lgkmcnt(0)
	v_add_f32_e32 v26, v31, v32
	v_add_f32_e32 v27, v33, v34
	v_rsq_f32_e32 v21, v21
	v_fmamk_f32 v22, v22, 0x3a800000, v1
	v_fmamk_f32 v23, v23, 0x3a800000, v1
	v_rsq_f32_e32 v25, v25
	v_fmamk_f32 v26, v26, 0x3a800000, v1
	v_fmamk_f32 v27, v27, 0x3a800000, v1
	v_rsq_f32_e32 v22, v22
	v_rsq_f32_e32 v23, v23
	v_rsq_f32_e32 v26, v26
	v_rsq_f32_e32 v27, v27
	s_lshr_b32 s7, s7, 26
	v_cvt_pkrtz_f16_f32 v143, v21, v25
	s_add_i32 s7, s6, s7
	v_or_b32_e32 v21, s2, v141
	v_cvt_pkrtz_f16_f32 v145, v22, v26
	v_cvt_pkrtz_f16_f32 v147, v23, v27
	s_ashr_i32 s15, s7, 6
	v_lshlrev_b32_e32 v22, 6, v21
	v_lshlrev_b32_e32 v23, 4, v14
	s_movk_i32 s7, 0x3c0
	v_lshlrev_b32_e32 v21, 2, v21
	v_and_or_b32 v22, v22, s7, v23
	s_lshl_b32 s7, s17, 13
	v_and_b32_e32 v21, 32, v21
	v_bitop3_b32 v21, v22, s7, v21 bitop3:0xde
	s_lshl_b32 s7, s16, 5
	s_and_b32 s7, s7, 0x60
	v_lshl_or_b32 v22, v141, 6, v23
	v_lshlrev_b32_e32 v23, 2, v141
	s_lshl_b32 s16, s7, 7
	v_and_b32_e32 v23, 32, v23
	s_add_i32 m0, s3, 0x18000
	v_lshl_add_u64 v[2:3], v[2:3], 0, s[62:63]
	v_bitop3_b32 v151, v22, s16, v23 bitop3:0xde
	s_waitcnt vmcnt(2)
	s_barrier
	global_load_lds_dwordx4 v[2:3], off
	v_lshl_add_u64 v[2:3], v[4:5], 0, s[62:63]
	s_add_i32 m0, s3, 0x1a000
	s_add_i32 s16, s3, 0x8000
	global_load_lds_dwordx4 v[2:3], off
	v_lshl_add_u64 v[2:3], v[10:11], 0, s[62:63]
	s_mov_b32 m0, s16
	s_add_i32 s17, s3, 0xa000
	global_load_lds_dwordx4 v[2:3], off
	v_lshl_add_u64 v[2:3], v[12:13], 0, s[62:63]
	s_mov_b32 m0, s17
	v_add_f32_e32 v28, v35, v36
	global_load_lds_dwordx4 v[2:3], off
	s_add_i32 m0, s3, 0x1c000
	v_lshl_add_u64 v[2:3], v[6:7], 0, s[62:63]
	global_load_lds_dwordx4 v[2:3], off
	v_lshl_add_u64 v[2:3], v[8:9], 0, s[62:63]
	s_add_i32 m0, s3, 0x1e000
	v_fmamk_f32 v24, v24, 0x3a800000, v1
	global_load_lds_dwordx4 v[2:3], off
	v_fmamk_f32 v28, v28, 0x3a800000, v1
	v_rsq_f32_e32 v24, v24
	v_rsq_f32_e32 v28, v28
	v_add_u32_e32 v2, v17, v15
	s_cmp_gt_i32 s6, 63
	v_add_lshl_u32 v2, v2, v16, 1
	v_mov_b32_e32 v3, v167
	s_waitcnt vmcnt(6)
	s_cselect_b64 s[86:87], -1, 0
	s_add_i32 s18, s15, -2
	v_lshl_add_u64 v[136:137], s[58:59], 0, v[2:3]
	v_add_u32_e32 v2, v20, v18
	s_cmpk_lt_u32 s19, 0x100
	v_add_lshl_u32 v2, v2, v19, 1
	v_readlane_b32 s56, v252, 19
	v_cvt_pkrtz_f16_f32 v149, v24, v28
	s_cselect_b64 s[88:89], -1, 0
	v_lshl_or_b32 v153, v14, 3, s7
	v_lshl_add_u64 v[138:139], s[58:59], 0, v[2:3]
	s_mov_b32 s19, 0
	v_add_u32_e32 v154, 0, v21
	v_readlane_b32 s22, v254, 14
	v_readlane_b32 s23, v254, 21
	v_readlane_b32 s57, v252, 20
	s_barrier
	s_mov_b32 s101, 0
	s_branch .LBB0_605
.LBB0_603:
	s_mov_b32 s101, 1
	s_mov_b64 s[6:7], 0

; #define PG8_STAGE(bufoff, gbase, voff) do { _Pragma("unroll") for (int _i = 0; _i < 2; ++_i) \
;         __builtin_amdgcn_global_load_lds((const unsigned*)((const char*)(gbase) + (voff)[_i]), (PG8_LAS unsigned*)(lds + (bufoff) + ldsw + _i * 8192), 16, 0, 0); } while (0)
; #define PG8_LDA(dst, b, h) do { _Pragma("unroll") for (int m = 0; m < 4; ++m) _Pragma("unroll") for (int k = 0; k < 2; ++k) dst[m][k] = *(const PG8_LAS bf16x8*)(lds + PG8_SA(b, h) + aoff + m * 2048 + k * 1024); } while (0)
; #define PG8_LDB(dst, b, h) do { _Pragma("unroll") for (int n = 0; n < 2; ++n) _Pragma("unroll") for (int k = 0; k < 2; ++k) dst[n][k] = *(const PG8_LAS bf16x8*)(lds + PG8_SB(b, h) + boff + n * 2048 + k * 1024); } while (0)
; #define PG8_MMA(ai, bj, At, Bt) do { __builtin_amdgcn_s_setprio(1); _Pragma("unroll") for (int m = 0; m < 4; ++m) _Pragma("unroll") for (int n = 0; n < 2; ++n) _Pragma("unroll") for (int k = 0; k < 2; ++k) \
;         acc[ai][bj][m][n] = __builtin_amdgcn_mfma_f32_16x16x32_bf16(Bt[n][k], At[m][k], acc[ai][bj][m][n], 0, 0, 0); __builtin_amdgcn_s_setprio(0); } while (0)
; #define PG8_WAIT_V(n) asm volatile("s_waitcnt vmcnt(" #n ")" ::: "memory")
; #define PG8_WAIT_L(n) asm volatile("s_waitcnt lgkmcnt(" #n ")" ::: "memory")
; #define PG8_BAR __builtin_amdgcn_s_barrier()
; #define PG8_SCHED __builtin_amdgcn_sched_barrier(0)
;     ...
;             PG8_LDB(B0, 0, 0); PG8_LDB(B1, 0, 1); PG8_SCHED; PG8_LDA(At, 0, 0); PG8_STAGE(PG8_SA(1, 1), a1 + hstepA, voffA);
;             PG8_WAIT_V(8); PG8_WAIT_L(0); PG8_BAR; PG8_MMA(0, 0, At, B0); PG8_MMA(0, 1, At, B1); PG8_BAR; PG8_SCHED;
;             PG8_LDA(At, 0, 1); PG8_STAGE(PG8_SB(0, 0), b2, voffB); PG8_STAGE(PG8_SB(0, 1), b2 + hstepB, voffB); PG8_STAGE(PG8_SA(0, 0), a2, voffA);
;             PG8_WAIT_V(8); PG8_WAIT_L(0); PG8_BAR; PG8_MMA(1, 0, At, B0); PG8_MMA(1, 1, At, B1); PG8_BAR; PG8_SCHED;
.LBB0_611:
	s_andn2_b64 vcc, exec, s[86:87]
	s_cbranch_vccnz .LBB0_614
	s_add_u32 s24, s8, 0x100
	s_addc_u32 s25, s9, 0
	s_add_u32 s6, s10, 0x80
	s_addc_u32 s7, s11, 0
	s_mov_b32 s8, 0
	s_add_i32 s10, s8, 2
	s_add_u32 s11, s6, 0x80
	s_addc_u32 s9, s7, 0
	s_add_i32 s27, 0, 0x10000
	s_cmp_eq_u32 s18, s8
	s_cselect_b32 s9, s41, s9
	s_cselect_b32 s8, s40, s11
	s_cselect_b32 s35, s91, s25
	s_cselect_b32 s34, s90, s24
	s_add_i32 s11, 0, 0x14000
	v_lshl_add_u64 v[164:165], s[6:7], 0, v[138:139]
	s_add_i32 m0, s3, 0xc000
	s_cmp_lg_u32 s101, 0
	s_cbranch_scc1 .Lgu_rd_done
	v_add_u32_e32 v140, s27, v151
	ds_read_b128 v[156:159], v140
	ds_read_b128 v[160:163], v140 offset:1024
	ds_read_b128 v[172:175], v140 offset:2048
	ds_read_b128 v[176:179], v140 offset:3072
	v_add_u32_e32 v140, s11, v151
	ds_read_b128 v[180:183], v140
	ds_read_b128 v[184:187], v140 offset:1024
	ds_read_b128 v[188:191], v140 offset:2048
	ds_read_b128 v[192:195], v140 offset:3072
	ds_read_b128 v[196:199], v154
	ds_read_b128 v[200:203], v154 offset:1024
	ds_read_b128 v[204:207], v154 offset:2048
	ds_read_b128 v[208:211], v154 offset:3072
	ds_read_b128 v[212:215], v154 offset:4096
	ds_read_b128 v[216:219], v154 offset:5120
	ds_read_b128 v[220:223], v154 offset:6144
	ds_read_b128 v[224:227], v154 offset:7168
.Lgu_rd_done:
	global_load_lds_dwordx4 v[164:165], off
	v_lshl_add_u64 v[164:165], s[6:7], 0, v[136:137]
	s_add_i32 m0, s3, 0xe000
	s_nop 0
	global_load_lds_dwordx4 v[164:165], off
	s_waitcnt vmcnt(8)
	s_waitcnt lgkmcnt(0)
	s_barrier
	s_waitcnt lgkmcnt(0)
	v_mfma_f32_16x16x32_bf16 v[126:129], v[156:159], v[196:199], 0
	v_mfma_f32_16x16x32_bf16 v[122:125], v[172:175], v[196:199], 0
	v_mfma_f32_16x16x32_bf16 v[110:113], v[156:159], v[204:207], 0
	v_mfma_f32_16x16x32_bf16 v[106:109], v[172:175], v[204:207], 0
	v_mfma_f32_16x16x32_bf16 v[94:97], v[156:159], v[212:215], 0
	v_mfma_f32_16x16x32_bf16 v[90:93], v[172:175], v[212:215], 0
	v_mfma_f32_16x16x32_bf16 v[78:81], v[156:159], v[220:223], 0
	v_mfma_f32_16x16x32_bf16 v[74:77], v[172:175], v[220:223], 0
	v_mfma_f32_16x16x32_bf16 v[126:129], v[160:163], v[200:203], v[126:129]
	v_mfma_f32_16x16x32_bf16 v[122:125], v[176:179], v[200:203], v[122:125]
	v_mfma_f32_16x16x32_bf16 v[110:113], v[160:163], v[208:211], v[110:113]
	v_mfma_f32_16x16x32_bf16 v[106:109], v[176:179], v[208:211], v[106:109]
	v_mfma_f32_16x16x32_bf16 v[94:97], v[160:163], v[216:219], v[94:97]
	v_mfma_f32_16x16x32_bf16 v[90:93], v[176:179], v[216:219], v[90:93]
	v_mfma_f32_16x16x32_bf16 v[78:81], v[160:163], v[224:227], v[78:81]
	v_mfma_f32_16x16x32_bf16 v[74:77], v[176:179], v[224:227], v[74:77]
	v_mfma_f32_16x16x32_bf16 v[118:121], v[180:183], v[196:199], 0
	v_mfma_f32_16x16x32_bf16 v[114:117], v[188:191], v[196:199], 0
	v_mfma_f32_16x16x32_bf16 v[102:105], v[180:183], v[204:207], 0
	v_mfma_f32_16x16x32_bf16 v[98:101], v[188:191], v[204:207], 0
	v_mfma_f32_16x16x32_bf16 v[86:89], v[180:183], v[212:215], 0
	v_mfma_f32_16x16x32_bf16 v[82:85], v[188:191], v[212:215], 0
	v_mfma_f32_16x16x32_bf16 v[70:73], v[180:183], v[220:223], 0
	v_mfma_f32_16x16x32_bf16 v[66:69], v[188:191], v[220:223], 0
	v_mfma_f32_16x16x32_bf16 v[118:121], v[184:187], v[200:203], v[118:121]
	v_mfma_f32_16x16x32_bf16 v[114:117], v[192:195], v[200:203], v[114:117]
	v_mfma_f32_16x16x32_bf16 v[102:105], v[184:187], v[208:211], v[102:105]
	v_mfma_f32_16x16x32_bf16 v[98:101], v[192:195], v[208:211], v[98:101]
	v_mfma_f32_16x16x32_bf16 v[86:89], v[184:187], v[216:219], v[86:89]
	v_mfma_f32_16x16x32_bf16 v[82:85], v[192:195], v[216:219], v[82:85]
	v_mfma_f32_16x16x32_bf16 v[70:73], v[184:187], v[224:227], v[70:73]
	v_mfma_f32_16x16x32_bf16 v[66:69], v[192:195], v[224:227], v[66:69]
	s_barrier
	s_add_i32 s27, s27, s0
	v_lshl_add_u64 v[164:165], s[34:35], 0, v[166:167]
	s_mov_b32 m0, s27
	ds_read_b128 v[196:199], v154 offset:16384
	ds_read_b128 v[200:203], v154 offset:17408
	ds_read_b128 v[204:207], v154 offset:18432
	ds_read_b128 v[208:211], v154 offset:19456
	ds_read_b128 v[212:215], v154 offset:20480
	ds_read_b128 v[216:219], v154 offset:21504
	ds_read_b128 v[220:223], v154 offset:22528
	ds_read_b128 v[224:227], v154 offset:23552
	global_load_lds_dwordx4 v[164:165], off
	s_add_i32 m0, s27, 0x2000
	v_lshl_add_u64 v[168:169], s[34:35], 0, v[130:131]
	s_add_u32 s34, s34, s58
	s_addc_u32 s35, s35, s59
	s_add_i32 s11, s11, s0
	global_load_lds_dwordx4 v[168:169], off
	v_lshl_add_u64 v[170:171], s[34:35], 0, v[166:167]
	s_mov_b32 m0, s11
	v_lshl_add_u64 v[228:229], s[34:35], 0, v[130:131]
	global_load_lds_dwordx4 v[170:171], off
	s_add_i32 m0, s11, 0x2000
	v_lshl_add_u64 v[230:231], s[8:9], 0, v[134:135]
	global_load_lds_dwordx4 v[228:229], off
	s_mov_b32 m0, s3
	v_lshl_add_u64 v[232:233], s[8:9], 0, v[132:133]
	global_load_lds_dwordx4 v[230:231], off
	s_mov_b32 m0, s12
	s_nop 0
	global_load_lds_dwordx4 v[232:233], off
	s_waitcnt vmcnt(8)
	s_waitcnt lgkmcnt(0)
	s_barrier
; #define PG8_STAGE(bufoff, gbase, voff) do { _Pragma("unroll") for (int _i = 0; _i < 2; ++_i) \
;         __builtin_amdgcn_global_load_lds((const unsigned*)((const char*)(gbase) + (voff)[_i]), (PG8_LAS unsigned*)(lds + (bufoff) + ldsw + _i * 8192), 16, 0, 0); } while (0)
; #define PG8_LDA(dst, b, h) do { _Pragma("unroll") for (int m = 0; m < 4; ++m) _Pragma("unroll") for (int k = 0; k < 2; ++k) dst[m][k] = *(const PG8_LAS bf16x8*)(lds + PG8_SA(b, h) + aoff + m * 2048 + k * 1024); } while (0)
; #define PG8_LDB(dst, b, h) do { _Pragma("unroll") for (int n = 0; n < 2; ++n) _Pragma("unroll") for (int k = 0; k < 2; ++k) dst[n][k] = *(const PG8_LAS bf16x8*)(lds + PG8_SB(b, h) + boff + n * 2048 + k * 1024); } while (0)
; #define PG8_MMA(ai, bj, At, Bt) do { __builtin_amdgcn_s_setprio(1); _Pragma("unroll") for (int m = 0; m < 4; ++m) _Pragma("unroll") for (int n = 0; n < 2; ++n) _Pragma("unroll") for (int k = 0; k < 2; ++k) \
;         acc[ai][bj][m][n] = __builtin_amdgcn_mfma_f32_16x16x32_bf16(Bt[n][k], At[m][k], acc[ai][bj][m][n], 0, 0, 0); __builtin_amdgcn_s_setprio(0); } while (0)
; #define PG8_WAIT_V(n) asm volatile("s_waitcnt vmcnt(" #n ")" ::: "memory")
; #define PG8_WAIT_L(n) asm volatile("s_waitcnt lgkmcnt(" #n ")" ::: "memory")
; #define PG8_BAR __builtin_amdgcn_s_barrier()
; #define PG8_SCHED __builtin_amdgcn_sched_barrier(0)
;     ...
;             PG8_WAIT_V(8); PG8_WAIT_L(0); PG8_BAR; PG8_MMA(1, 0, At, B0); PG8_MMA(1, 1, At, B1); PG8_BAR; PG8_SCHED;
;             PG8_LDB(B0, 1, 0); PG8_LDB(B1, 1, 1); PG8_SCHED; PG8_LDA(At, 1, 0); PG8_STAGE(PG8_SA(0, 1), a2 + hstepA, voffA);
;             PG8_WAIT_V(8); PG8_WAIT_L(0); PG8_BAR; PG8_MMA(0, 0, At, B0); PG8_MMA(0, 1, At, B1); PG8_BAR; PG8_SCHED;
	s_waitcnt lgkmcnt(0)
	v_mfma_f32_16x16x32_bf16 v[62:65], v[156:159], v[196:199], 0
	v_mfma_f32_16x16x32_bf16 v[58:61], v[172:175], v[196:199], 0
	v_mfma_f32_16x16x32_bf16 v[46:49], v[156:159], v[204:207], 0
	v_mfma_f32_16x16x32_bf16 v[42:45], v[172:175], v[204:207], 0
	v_mfma_f32_16x16x32_bf16 v[30:33], v[156:159], v[212:215], 0
	v_mfma_f32_16x16x32_bf16 v[26:29], v[172:175], v[212:215], 0
	v_mfma_f32_16x16x32_bf16 v[14:17], v[156:159], v[220:223], 0
	v_mfma_f32_16x16x32_bf16 v[10:13], v[172:175], v[220:223], 0
	v_mfma_f32_16x16x32_bf16 v[62:65], v[160:163], v[200:203], v[62:65]
	v_mfma_f32_16x16x32_bf16 v[58:61], v[176:179], v[200:203], v[58:61]
	v_mfma_f32_16x16x32_bf16 v[46:49], v[160:163], v[208:211], v[46:49]
	v_mfma_f32_16x16x32_bf16 v[42:45], v[176:179], v[208:211], v[42:45]
	v_mfma_f32_16x16x32_bf16 v[30:33], v[160:163], v[216:219], v[30:33]
	v_mfma_f32_16x16x32_bf16 v[26:29], v[176:179], v[216:219], v[26:29]
	v_mfma_f32_16x16x32_bf16 v[14:17], v[160:163], v[224:227], v[14:17]
	v_mfma_f32_16x16x32_bf16 v[10:13], v[176:179], v[224:227], v[10:13]
	v_mfma_f32_16x16x32_bf16 v[54:57], v[180:183], v[196:199], 0
	v_mfma_f32_16x16x32_bf16 v[50:53], v[188:191], v[196:199], 0
	v_mfma_f32_16x16x32_bf16 v[38:41], v[180:183], v[204:207], 0
	v_mfma_f32_16x16x32_bf16 v[34:37], v[188:191], v[204:207], 0
	v_mfma_f32_16x16x32_bf16 v[22:25], v[180:183], v[212:215], 0
	v_mfma_f32_16x16x32_bf16 v[18:21], v[188:191], v[212:215], 0
	v_mfma_f32_16x16x32_bf16 v[6:9], v[180:183], v[220:223], 0
	v_mfma_f32_16x16x32_bf16 v[2:5], v[188:191], v[220:223], 0
	v_mfma_f32_16x16x32_bf16 v[54:57], v[184:187], v[200:203], v[54:57]
	v_mfma_f32_16x16x32_bf16 v[50:53], v[192:195], v[200:203], v[50:53]
	v_mfma_f32_16x16x32_bf16 v[38:41], v[184:187], v[208:211], v[38:41]
	v_mfma_f32_16x16x32_bf16 v[34:37], v[192:195], v[208:211], v[34:37]
	v_mfma_f32_16x16x32_bf16 v[22:25], v[184:187], v[216:219], v[22:25]
	v_mfma_f32_16x16x32_bf16 v[18:21], v[192:195], v[216:219], v[18:21]
	v_mfma_f32_16x16x32_bf16 v[6:9], v[184:187], v[224:227], v[6:9]
	v_mfma_f32_16x16x32_bf16 v[2:5], v[192:195], v[224:227], v[2:5]
	s_barrier
	s_add_i32 s11, 0, 0x18000
	v_add_u32_e32 v140, s11, v151
	s_add_i32 s27, 0, 0x1c000
	ds_read_b128 v[156:159], v140
	ds_read_b128 v[160:163], v140 offset:1024
	ds_read_b128 v[172:175], v140 offset:2048
	ds_read_b128 v[176:179], v140 offset:3072
	v_add_u32_e32 v140, s27, v151
	ds_read_b128 v[180:183], v140
	ds_read_b128 v[184:187], v140 offset:1024
	ds_read_b128 v[188:191], v140 offset:2048
	ds_read_b128 v[192:195], v140 offset:3072
	s_add_u32 s8, s8, s58
	s_addc_u32 s9, s9, s59
	s_mov_b32 m0, s13
	v_lshl_add_u64 v[234:235], s[8:9], 0, v[134:135]
	ds_read_b128 v[196:199], v154 offset:32768
	ds_read_b128 v[200:203], v154 offset:33792
	ds_read_b128 v[204:207], v154 offset:34816
	ds_read_b128 v[208:211], v154 offset:35840
	ds_read_b128 v[212:215], v154 offset:36864
	ds_read_b128 v[216:219], v154 offset:37888
	ds_read_b128 v[220:223], v154 offset:38912
	ds_read_b128 v[224:227], v154 offset:39936
	global_load_lds_dwordx4 v[234:235], off
	v_lshl_add_u64 v[234:235], s[8:9], 0, v[132:133]
	s_mov_b32 m0, s14
	s_nop 0
	global_load_lds_dwordx4 v[234:235], off
	s_waitcnt vmcnt(8)
	s_waitcnt lgkmcnt(0)
	s_barrier
	s_waitcnt lgkmcnt(0)
	v_mfma_f32_16x16x32_bf16 v[126:129], v[156:159], v[196:199], v[126:129]
	v_mfma_f32_16x16x32_bf16 v[122:125], v[172:175], v[196:199], v[122:125]
	v_mfma_f32_16x16x32_bf16 v[110:113], v[156:159], v[204:207], v[110:113]
	v_mfma_f32_16x16x32_bf16 v[106:109], v[172:175], v[204:207], v[106:109]
	v_mfma_f32_16x16x32_bf16 v[94:97], v[156:159], v[212:215], v[94:97]
	v_mfma_f32_16x16x32_bf16 v[90:93], v[172:175], v[212:215], v[90:93]
	v_mfma_f32_16x16x32_bf16 v[78:81], v[156:159], v[220:223], v[78:81]
	v_mfma_f32_16x16x32_bf16 v[74:77], v[172:175], v[220:223], v[74:77]
	v_mfma_f32_16x16x32_bf16 v[126:129], v[160:163], v[200:203], v[126:129]
	v_mfma_f32_16x16x32_bf16 v[122:125], v[176:179], v[200:203], v[122:125]
	v_mfma_f32_16x16x32_bf16 v[110:113], v[160:163], v[208:211], v[110:113]
	v_mfma_f32_16x16x32_bf16 v[106:109], v[176:179], v[208:211], v[106:109]
	v_mfma_f32_16x16x32_bf16 v[94:97], v[160:163], v[216:219], v[94:97]
	v_mfma_f32_16x16x32_bf16 v[90:93], v[176:179], v[216:219], v[90:93]
	v_mfma_f32_16x16x32_bf16 v[78:81], v[160:163], v[224:227], v[78:81]
	v_mfma_f32_16x16x32_bf16 v[74:77], v[176:179], v[224:227], v[74:77]
	v_mfma_f32_16x16x32_bf16 v[118:121], v[180:183], v[196:199], v[118:121]
	v_mfma_f32_16x16x32_bf16 v[114:117], v[188:191], v[196:199], v[114:117]
	v_mfma_f32_16x16x32_bf16 v[102:105], v[180:183], v[204:207], v[102:105]
	v_mfma_f32_16x16x32_bf16 v[98:101], v[188:191], v[204:207], v[98:101]
	v_mfma_f32_16x16x32_bf16 v[86:89], v[180:183], v[212:215], v[86:89]
	v_mfma_f32_16x16x32_bf16 v[82:85], v[188:191], v[212:215], v[82:85]
	v_mfma_f32_16x16x32_bf16 v[70:73], v[180:183], v[220:223], v[70:73]
	v_mfma_f32_16x16x32_bf16 v[66:69], v[188:191], v[220:223], v[66:69]
	v_mfma_f32_16x16x32_bf16 v[118:121], v[184:187], v[200:203], v[118:121]
	v_mfma_f32_16x16x32_bf16 v[114:117], v[192:195], v[200:203], v[114:117]
	v_mfma_f32_16x16x32_bf16 v[102:105], v[184:187], v[208:211], v[102:105]
	v_mfma_f32_16x16x32_bf16 v[98:101], v[192:195], v[208:211], v[98:101]
	v_mfma_f32_16x16x32_bf16 v[86:89], v[184:187], v[216:219], v[86:89]
	v_mfma_f32_16x16x32_bf16 v[82:85], v[192:195], v[216:219], v[82:85]
	v_mfma_f32_16x16x32_bf16 v[70:73], v[184:187], v[224:227], v[70:73]
	v_mfma_f32_16x16x32_bf16 v[66:69], v[192:195], v[224:227], v[66:69]
	s_barrier
; #define PG8_STAGE(bufoff, gbase, voff) do { _Pragma("unroll") for (int _i = 0; _i < 2; ++_i) \
;         __builtin_amdgcn_global_load_lds((const unsigned*)((const char*)(gbase) + (voff)[_i]), (PG8_LAS unsigned*)(lds + (bufoff) + ldsw + _i * 8192), 16, 0, 0); } while (0)
; #define PG8_LDA(dst, b, h) do { _Pragma("unroll") for (int m = 0; m < 4; ++m) _Pragma("unroll") for (int k = 0; k < 2; ++k) dst[m][k] = *(const PG8_LAS bf16x8*)(lds + PG8_SA(b, h) + aoff + m * 2048 + k * 1024); } while (0)
; #define PG8_LDB(dst, b, h) do { _Pragma("unroll") for (int n = 0; n < 2; ++n) _Pragma("unroll") for (int k = 0; k < 2; ++k) dst[n][k] = *(const PG8_LAS bf16x8*)(lds + PG8_SB(b, h) + boff + n * 2048 + k * 1024); } while (0)
; #define PG8_MMA(ai, bj, At, Bt) do { __builtin_amdgcn_s_setprio(1); _Pragma("unroll") for (int m = 0; m < 4; ++m) _Pragma("unroll") for (int n = 0; n < 2; ++n) _Pragma("unroll") for (int k = 0; k < 2; ++k) \
;         acc[ai][bj][m][n] = __builtin_amdgcn_mfma_f32_16x16x32_bf16(Bt[n][k], At[m][k], acc[ai][bj][m][n], 0, 0, 0); __builtin_amdgcn_s_setprio(0); } while (0)
; #define PG8_WAIT_V(n) asm volatile("s_waitcnt vmcnt(" #n ")" ::: "memory")
; #define PG8_WAIT_L(n) asm volatile("s_waitcnt lgkmcnt(" #n ")" ::: "memory")
; #define PG8_BAR __builtin_amdgcn_s_barrier()
; #define PG8_SCHED __builtin_amdgcn_sched_barrier(0)
;     ...
;             PG8_LDB(B0, 1, 0); PG8_LDB(B1, 1, 1); PG8_SCHED; PG8_LDA(At, 1, 0); PG8_STAGE(PG8_SA(0, 1), a2 + hstepA, voffA);
;             PG8_WAIT_V(8); PG8_WAIT_L(0); PG8_BAR; PG8_MMA(0, 0, At, B0); PG8_MMA(0, 1, At, B1); PG8_BAR; PG8_SCHED;
;             PG8_LDA(At, 1, 1); PG8_STAGE(PG8_SB(1, 0), b3, voffB); PG8_STAGE(PG8_SB(1, 1), b3 + hstepB, voffB); PG8_STAGE(PG8_SA(1, 0), a3, voffA);
;             PG8_WAIT_V(8); PG8_WAIT_L(0); PG8_BAR; PG8_MMA(1, 0, At, B0); PG8_MMA(1, 1, At, B1); PG8_BAR; PG8_SCHED;
	s_add_i32 s8, s11, s0
	v_lshl_add_u64 v[164:165], v[164:165], 0, s[62:63]
	s_mov_b32 m0, s8
	ds_read_b128 v[196:199], v154 offset:49152
	ds_read_b128 v[200:203], v154 offset:50176
	ds_read_b128 v[204:207], v154 offset:51200
	ds_read_b128 v[208:211], v154 offset:52224
	ds_read_b128 v[212:215], v154 offset:53248
	ds_read_b128 v[216:219], v154 offset:54272
	ds_read_b128 v[220:223], v154 offset:55296
	ds_read_b128 v[224:227], v154 offset:56320
	global_load_lds_dwordx4 v[164:165], off
	v_lshl_add_u64 v[164:165], v[168:169], 0, s[62:63]
	s_add_i32 m0, s8, 0x2000
	s_add_i32 s8, s27, s0
	global_load_lds_dwordx4 v[164:165], off
	v_lshl_add_u64 v[164:165], v[170:171], 0, s[62:63]
	s_mov_b32 m0, s8
	s_nop 0
	global_load_lds_dwordx4 v[164:165], off
	v_lshl_add_u64 v[164:165], v[228:229], 0, s[62:63]
	s_add_i32 m0, s8, 0x2000
	s_nop 0
	global_load_lds_dwordx4 v[164:165], off
	v_lshl_add_u64 v[164:165], v[230:231], 0, s[62:63]
	s_mov_b32 m0, s16
	s_nop 0
	global_load_lds_dwordx4 v[164:165], off
	v_lshl_add_u64 v[164:165], v[232:233], 0, s[62:63]
	s_mov_b32 m0, s17
	s_nop 0
	global_load_lds_dwordx4 v[164:165], off
	s_waitcnt vmcnt(8)
	s_waitcnt lgkmcnt(0)
	s_barrier
	s_waitcnt lgkmcnt(0)
	v_mfma_f32_16x16x32_bf16 v[62:65], v[156:159], v[196:199], v[62:65]
	v_mfma_f32_16x16x32_bf16 v[58:61], v[172:175], v[196:199], v[58:61]
	v_mfma_f32_16x16x32_bf16 v[46:49], v[156:159], v[204:207], v[46:49]
	v_mfma_f32_16x16x32_bf16 v[42:45], v[172:175], v[204:207], v[42:45]
	v_mfma_f32_16x16x32_bf16 v[30:33], v[156:159], v[212:215], v[30:33]
	v_mfma_f32_16x16x32_bf16 v[26:29], v[172:175], v[212:215], v[26:29]
	v_mfma_f32_16x16x32_bf16 v[14:17], v[156:159], v[220:223], v[14:17]
	v_mfma_f32_16x16x32_bf16 v[10:13], v[172:175], v[220:223], v[10:13]
	v_mfma_f32_16x16x32_bf16 v[62:65], v[160:163], v[200:203], v[62:65]
	v_mfma_f32_16x16x32_bf16 v[58:61], v[176:179], v[200:203], v[58:61]
	v_mfma_f32_16x16x32_bf16 v[46:49], v[160:163], v[208:211], v[46:49]
	v_mfma_f32_16x16x32_bf16 v[42:45], v[176:179], v[208:211], v[42:45]
	v_mfma_f32_16x16x32_bf16 v[30:33], v[160:163], v[216:219], v[30:33]
	v_mfma_f32_16x16x32_bf16 v[26:29], v[176:179], v[216:219], v[26:29]
	v_mfma_f32_16x16x32_bf16 v[14:17], v[160:163], v[224:227], v[14:17]
	v_mfma_f32_16x16x32_bf16 v[10:13], v[176:179], v[224:227], v[10:13]
	v_mfma_f32_16x16x32_bf16 v[54:57], v[180:183], v[196:199], v[54:57]
	v_mfma_f32_16x16x32_bf16 v[50:53], v[188:191], v[196:199], v[50:53]
	v_mfma_f32_16x16x32_bf16 v[38:41], v[180:183], v[204:207], v[38:41]
	v_mfma_f32_16x16x32_bf16 v[34:37], v[188:191], v[204:207], v[34:37]
	v_mfma_f32_16x16x32_bf16 v[22:25], v[180:183], v[212:215], v[22:25]
	v_mfma_f32_16x16x32_bf16 v[18:21], v[188:191], v[212:215], v[18:21]
	v_mfma_f32_16x16x32_bf16 v[6:9], v[180:183], v[220:223], v[6:9]
	v_mfma_f32_16x16x32_bf16 v[2:5], v[188:191], v[220:223], v[2:5]
	v_mfma_f32_16x16x32_bf16 v[54:57], v[184:187], v[200:203], v[54:57]
	v_mfma_f32_16x16x32_bf16 v[50:53], v[192:195], v[200:203], v[50:53]
	v_mfma_f32_16x16x32_bf16 v[38:41], v[184:187], v[208:211], v[38:41]
	v_mfma_f32_16x16x32_bf16 v[34:37], v[192:195], v[208:211], v[34:37]
	v_mfma_f32_16x16x32_bf16 v[22:25], v[184:187], v[216:219], v[22:25]
	v_mfma_f32_16x16x32_bf16 v[18:21], v[192:195], v[216:219], v[18:21]
	v_mfma_f32_16x16x32_bf16 v[6:9], v[184:187], v[224:227], v[6:9]
	v_mfma_f32_16x16x32_bf16 v[2:5], v[192:195], v[224:227], v[2:5]
	s_barrier
	s_add_u32 s24, s24, 0x100
	s_addc_u32 s25, s25, 0
	s_add_u32 s6, s6, 0x100
	s_addc_u32 s7, s7, 0
	s_cmp_ge_i32 s10, s15
	s_mov_b32 s8, s10
	s_cbranch_scc1 .LBB0_614

; __device__ __forceinline__ unsigned cvt_pk_bf16(float lo, float hi) { f32x2_t v = {lo, hi}; bf16x2_t b = __builtin_convertvector(v, bf16x2_t); return __builtin_bit_cast(unsigned, b); }
; __device__ __forceinline__ float silu_mul(float a, float b) { return a * b * __builtin_amdgcn_rcpf(1.0f + __builtin_amdgcn_exp2f(a * -1.4426950408889634f)); }
;     __device__ __forceinline__ void operator()(const f32x4 (&acc)[2][2][4][2], const Unit& u, int wr, int wc, int fr, int fq, const float (&rr)[2][4]) const {
;         const int row0 = u.pm * BM + wr * 64 + fr, col0 = u.pn * 128 + wc * 32 + 8 * fq;
; #pragma unroll
;         for (int ai = 0; ai < 2; ++ai)
; #pragma unroll
;             for (int m = 0; m < 4; ++m) { const int row = row0 + ai * HALF + m * 16; const float r = rr[ai][m];
;                 const f32x4 g0 = acc[ai][0][m][0] * r, g1 = acc[ai][0][m][1] * r, u0 = acc[ai][1][m][0] * r, u1 = acc[ai][1][m][1] * r;
;                 u32x4 w; w.x = cvt_pk_bf16(silu_mul(g0[0], u0[0]), silu_mul(g0[1], u0[1])); w.y = cvt_pk_bf16(silu_mul(g0[2], u0[2]), silu_mul(g0[3], u0[3]));
;                 w.z = cvt_pk_bf16(silu_mul(g1[0], u1[0]), silu_mul(g1[1], u1[1])); w.w = cvt_pk_bf16(silu_mul(g1[2], u1[2]), silu_mul(g1[3], u1[3]));
;                 *(u32x4*)(O + (size_t)row * ldc + col0) = w; }
.LBB0_616:
	v_add_u32_e32 v140, 0x10000, v151
	ds_read_b128 v[156:159], v140
	ds_read_b128 v[160:163], v140 offset:1024
	ds_read_b128 v[172:175], v140 offset:2048
	ds_read_b128 v[176:179], v140 offset:3072
	v_add_u32_e32 v140, 0x14000, v151
	ds_read_b128 v[180:183], v140
	ds_read_b128 v[184:187], v140 offset:1024
	ds_read_b128 v[188:191], v140 offset:2048
	ds_read_b128 v[192:195], v140 offset:3072
	ds_read_b128 v[196:199], v154
	ds_read_b128 v[200:203], v154 offset:1024
	ds_read_b128 v[204:207], v154 offset:2048
	ds_read_b128 v[208:211], v154 offset:3072
	ds_read_b128 v[212:215], v154 offset:4096
	ds_read_b128 v[216:219], v154 offset:5120
	ds_read_b128 v[220:223], v154 offset:6144
	ds_read_b128 v[224:227], v154 offset:7168
	s_lshl_b32 s6, s23, 8
	s_add_i32 s6, s6, s2
	s_movk_i32 s8, 0x1600
	v_and_b32_e32 v155, 24, v153
	v_lshl_or_b32 v155, v155, 1, v141
	v_lshrrev_b32_e32 v150, 2, v155
	v_and_b32_e32 v152, 3, v155
	v_lshrrev_b32_e32 v146, 4, v155
	v_lshrrev_b32_e32 v148, 2, v141
	v_xor_b32_e32 v146, v146, v148
	v_lshlrev_b32_e32 v146, 4, v146
	v_lshl_or_b32 v146, v141, 6, v146
	v_add_u32_e32 v146, s3, v146
	v_add_u32_e32 v146, 0x23000, v146
	v_lshrrev_b32_e32 v148, 2, v150
	v_xor_b32_e32 v148, v148, v152
	v_lshlrev_b32_e32 v148, 4, v148
	v_lshl_or_b32 v148, v150, 6, v148
	v_add_u32_e32 v148, s3, v148
	v_add_u32_e32 v148, 0x23000, v148
	v_add_u32_e32 v150, s6, v150
	v_mul_lo_u32 v150, v150, s8
	v_and_b32_e32 v244, 0x60, v153
	v_lshl_or_b32 v244, s22, 7, v244
	v_lshlrev_b32_e32 v244, 1, v244
	v_lshl_or_b32 v244, v152, 4, v244
	v_mov_b32_e32 v245, 0
	v_add_u32_e32 v244, v244, v150
	v_mov_b32_e32 v240, 1.0
	v_mov_b32_e32 v241, 1.0
	v_lshl_add_u64 v[244:245], s[56:57], 0, v[244:245]
	v_cvt_f32_f16_e32 v140, v143
	v_pk_mul_f32 v[118:119], v[126:127], v[118:119]
	v_pk_mul_f32 v[120:121], v[128:129], v[120:121]
	v_pk_mul_f32 v[114:115], v[122:123], v[114:115]
	v_pk_mul_f32 v[116:117], v[124:125], v[116:117]
	v_mul_f32_e32 v142, 0xbfb8aa3b, v140
	v_mul_f32_e32 v144, v140, v140
	v_pk_mul_f32 v[126:127], v[126:127], v[142:143] op_sel_hi:[1,0]
	v_pk_mul_f32 v[128:129], v[128:129], v[142:143] op_sel_hi:[1,0]
	v_pk_mul_f32 v[122:123], v[122:123], v[142:143] op_sel_hi:[1,0]
	v_pk_mul_f32 v[124:125], v[124:125], v[142:143] op_sel_hi:[1,0]
	v_exp_f32_e32 v126, v126
	v_exp_f32_e32 v127, v127
	v_exp_f32_e32 v128, v128
	v_exp_f32_e32 v129, v129
	v_exp_f32_e32 v122, v122
	v_exp_f32_e32 v123, v123
	v_exp_f32_e32 v124, v124
	v_exp_f32_e32 v125, v125
	v_pk_mul_f32 v[118:119], v[118:119], v[144:145] op_sel_hi:[1,0]
	v_pk_mul_f32 v[120:121], v[120:121], v[144:145] op_sel_hi:[1,0]
	v_pk_mul_f32 v[114:115], v[114:115], v[144:145] op_sel_hi:[1,0]
	v_pk_mul_f32 v[116:117], v[116:117], v[144:145] op_sel_hi:[1,0]
	v_pk_add_f32 v[126:127], v[126:127], v[240:241]
	v_pk_add_f32 v[128:129], v[128:129], v[240:241]
	v_pk_add_f32 v[122:123], v[122:123], v[240:241]
	v_pk_add_f32 v[124:125], v[124:125], v[240:241]
	v_rcp_f32_e32 v126, v126
	v_rcp_f32_e32 v127, v127
	v_rcp_f32_e32 v128, v128
	v_rcp_f32_e32 v129, v129
	v_rcp_f32_e32 v122, v122
	v_rcp_f32_e32 v123, v123
	v_rcp_f32_e32 v124, v124
	v_rcp_f32_e32 v125, v125
	s_nop 0
	v_pk_mul_f32 v[118:119], v[118:119], v[126:127]
	v_pk_mul_f32 v[120:121], v[120:121], v[128:129]
	v_pk_mul_f32 v[114:115], v[114:115], v[122:123]
	v_pk_mul_f32 v[116:117], v[116:117], v[124:125]
	v_cvt_pk_bf16_f32 v118, v118, v119
	v_cvt_pk_bf16_f32 v119, v120, v121
	v_cvt_pk_bf16_f32 v120, v114, v115
	v_cvt_pk_bf16_f32 v121, v116, v117
	ds_write_b128 v146, v[118:121]
	ds_read_b128 v[126:129], v148
	v_cvt_f32_f16_e32 v140, v145
	v_pk_mul_f32 v[102:103], v[110:111], v[102:103]
	v_pk_mul_f32 v[104:105], v[112:113], v[104:105]
	v_pk_mul_f32 v[98:99], v[106:107], v[98:99]
	v_pk_mul_f32 v[100:101], v[108:109], v[100:101]
	v_mul_f32_e32 v142, 0xbfb8aa3b, v140
	v_mul_f32_e32 v144, v140, v140
	v_pk_mul_f32 v[110:111], v[110:111], v[142:143] op_sel_hi:[1,0]
	v_pk_mul_f32 v[112:113], v[112:113], v[142:143] op_sel_hi:[1,0]
	v_pk_mul_f32 v[106:107], v[106:107], v[142:143] op_sel_hi:[1,0]
	v_pk_mul_f32 v[108:109], v[108:109], v[142:143] op_sel_hi:[1,0]
	v_exp_f32_e32 v110, v110
	v_exp_f32_e32 v111, v111
	v_exp_f32_e32 v112, v112
	v_exp_f32_e32 v113, v113
	v_exp_f32_e32 v106, v106
	v_exp_f32_e32 v107, v107
	v_exp_f32_e32 v108, v108
	v_exp_f32_e32 v109, v109
	v_pk_mul_f32 v[102:103], v[102:103], v[144:145] op_sel_hi:[1,0]
	v_pk_mul_f32 v[104:105], v[104:105], v[144:145] op_sel_hi:[1,0]
	v_pk_mul_f32 v[98:99], v[98:99], v[144:145] op_sel_hi:[1,0]
	v_pk_mul_f32 v[100:101], v[100:101], v[144:145] op_sel_hi:[1,0]
	v_pk_add_f32 v[110:111], v[110:111], v[240:241]
	v_pk_add_f32 v[112:113], v[112:113], v[240:241]
	v_pk_add_f32 v[106:107], v[106:107], v[240:241]
	v_pk_add_f32 v[108:109], v[108:109], v[240:241]
	v_rcp_f32_e32 v110, v110
	v_rcp_f32_e32 v111, v111
	v_rcp_f32_e32 v112, v112
	v_rcp_f32_e32 v113, v113
	v_rcp_f32_e32 v106, v106
	v_rcp_f32_e32 v107, v107
	v_rcp_f32_e32 v108, v108
	v_rcp_f32_e32 v109, v109
	s_waitcnt lgkmcnt(0)
; __device__ __forceinline__ unsigned cvt_pk_bf16(float lo, float hi) { f32x2_t v = {lo, hi}; bf16x2_t b = __builtin_convertvector(v, bf16x2_t); return __builtin_bit_cast(unsigned, b); }
; __device__ __forceinline__ float silu_mul(float a, float b) { return a * b * __builtin_amdgcn_rcpf(1.0f + __builtin_amdgcn_exp2f(a * -1.4426950408889634f)); }
;     __device__ __forceinline__ void operator()(const f32x4 (&acc)[2][2][4][2], const Unit& u, int wr, int wc, int fr, int fq, const float (&rr)[2][4]) const {
;     ...
;         for (int ai = 0; ai < 2; ++ai)
; #pragma unroll
;             for (int m = 0; m < 4; ++m) { const int row = row0 + ai * HALF + m * 16; const float r = rr[ai][m];
;                 const f32x4 g0 = acc[ai][0][m][0] * r, g1 = acc[ai][0][m][1] * r, u0 = acc[ai][1][m][0] * r, u1 = acc[ai][1][m][1] * r;
;                 u32x4 w; w.x = cvt_pk_bf16(silu_mul(g0[0], u0[0]), silu_mul(g0[1], u0[1])); w.y = cvt_pk_bf16(silu_mul(g0[2], u0[2]), silu_mul(g0[3], u0[3]));
;                 w.z = cvt_pk_bf16(silu_mul(g1[0], u1[0]), silu_mul(g1[1], u1[1])); w.w = cvt_pk_bf16(silu_mul(g1[2], u1[2]), silu_mul(g1[3], u1[3]));
;                 *(u32x4*)(O + (size_t)row * ldc + col0) = w; }
	global_store_dwordx4 v[244:245], v[126:129], off
	v_pk_mul_f32 v[102:103], v[102:103], v[110:111]
	v_pk_mul_f32 v[104:105], v[104:105], v[112:113]
	v_pk_mul_f32 v[98:99], v[98:99], v[106:107]
	v_pk_mul_f32 v[100:101], v[100:101], v[108:109]
	v_cvt_pk_bf16_f32 v102, v102, v103
	v_cvt_pk_bf16_f32 v103, v104, v105
	v_cvt_pk_bf16_f32 v104, v98, v99
	v_cvt_pk_bf16_f32 v105, v100, v101
	ds_write_b128 v146, v[102:105]
	ds_read_b128 v[110:113], v148
	v_cvt_f32_f16_e32 v140, v147
	v_pk_mul_f32 v[86:87], v[94:95], v[86:87]
	v_pk_mul_f32 v[88:89], v[96:97], v[88:89]
	v_pk_mul_f32 v[82:83], v[90:91], v[82:83]
	v_pk_mul_f32 v[84:85], v[92:93], v[84:85]
	v_mul_f32_e32 v142, 0xbfb8aa3b, v140
	v_mul_f32_e32 v144, v140, v140
	v_pk_mul_f32 v[94:95], v[94:95], v[142:143] op_sel_hi:[1,0]
	v_pk_mul_f32 v[96:97], v[96:97], v[142:143] op_sel_hi:[1,0]
	v_pk_mul_f32 v[90:91], v[90:91], v[142:143] op_sel_hi:[1,0]
	v_pk_mul_f32 v[92:93], v[92:93], v[142:143] op_sel_hi:[1,0]
	v_exp_f32_e32 v94, v94
	v_exp_f32_e32 v95, v95
	v_exp_f32_e32 v96, v96
	v_exp_f32_e32 v97, v97
	v_exp_f32_e32 v90, v90
	v_exp_f32_e32 v91, v91
	v_exp_f32_e32 v92, v92
	v_exp_f32_e32 v93, v93
	v_pk_mul_f32 v[86:87], v[86:87], v[144:145] op_sel_hi:[1,0]
	v_pk_mul_f32 v[88:89], v[88:89], v[144:145] op_sel_hi:[1,0]
	v_pk_mul_f32 v[82:83], v[82:83], v[144:145] op_sel_hi:[1,0]
	v_pk_mul_f32 v[84:85], v[84:85], v[144:145] op_sel_hi:[1,0]
	v_pk_add_f32 v[94:95], v[94:95], v[240:241]
	v_pk_add_f32 v[96:97], v[96:97], v[240:241]
	v_pk_add_f32 v[90:91], v[90:91], v[240:241]
	v_pk_add_f32 v[92:93], v[92:93], v[240:241]
	v_rcp_f32_e32 v94, v94
	v_rcp_f32_e32 v95, v95
	v_rcp_f32_e32 v96, v96
	v_rcp_f32_e32 v97, v97
	v_rcp_f32_e32 v90, v90
	v_rcp_f32_e32 v91, v91
	v_rcp_f32_e32 v92, v92
	v_rcp_f32_e32 v93, v93
	s_mov_b64 s[6:7], 0x16000
	v_lshl_add_u64 v[244:245], v[244:245], 0, s[6:7]
	s_waitcnt lgkmcnt(0)
	global_store_dwordx4 v[244:245], v[110:113], off
	v_pk_mul_f32 v[86:87], v[86:87], v[94:95]
	v_pk_mul_f32 v[88:89], v[88:89], v[96:97]
	v_pk_mul_f32 v[82:83], v[82:83], v[90:91]
	v_pk_mul_f32 v[84:85], v[84:85], v[92:93]
	v_cvt_pk_bf16_f32 v86, v86, v87
	v_cvt_pk_bf16_f32 v87, v88, v89
	v_cvt_pk_bf16_f32 v88, v82, v83
	v_cvt_pk_bf16_f32 v89, v84, v85
	ds_write_b128 v146, v[86:89]
	ds_read_b128 v[94:97], v148
	v_cvt_f32_f16_e32 v140, v149
	v_pk_mul_f32 v[70:71], v[78:79], v[70:71]
	v_pk_mul_f32 v[72:73], v[80:81], v[72:73]
	v_pk_mul_f32 v[66:67], v[74:75], v[66:67]
	v_pk_mul_f32 v[68:69], v[76:77], v[68:69]
	v_mul_f32_e32 v142, 0xbfb8aa3b, v140
	v_mul_f32_e32 v144, v140, v140
	v_pk_mul_f32 v[78:79], v[78:79], v[142:143] op_sel_hi:[1,0]
	v_pk_mul_f32 v[80:81], v[80:81], v[142:143] op_sel_hi:[1,0]
	v_pk_mul_f32 v[74:75], v[74:75], v[142:143] op_sel_hi:[1,0]
	v_pk_mul_f32 v[76:77], v[76:77], v[142:143] op_sel_hi:[1,0]
	v_exp_f32_e32 v78, v78
	v_exp_f32_e32 v79, v79
	v_exp_f32_e32 v80, v80
	v_exp_f32_e32 v81, v81
	v_exp_f32_e32 v74, v74
	v_exp_f32_e32 v75, v75
	v_exp_f32_e32 v76, v76
	v_exp_f32_e32 v77, v77
	v_pk_mul_f32 v[70:71], v[70:71], v[144:145] op_sel_hi:[1,0]
	v_pk_mul_f32 v[72:73], v[72:73], v[144:145] op_sel_hi:[1,0]
	v_pk_mul_f32 v[66:67], v[66:67], v[144:145] op_sel_hi:[1,0]
	v_pk_mul_f32 v[68:69], v[68:69], v[144:145] op_sel_hi:[1,0]
	v_pk_add_f32 v[78:79], v[78:79], v[240:241]
	v_pk_add_f32 v[80:81], v[80:81], v[240:241]
	v_pk_add_f32 v[74:75], v[74:75], v[240:241]
	v_pk_add_f32 v[76:77], v[76:77], v[240:241]
	v_rcp_f32_e32 v78, v78
	v_rcp_f32_e32 v79, v79
	v_rcp_f32_e32 v80, v80
	v_rcp_f32_e32 v81, v81
	v_rcp_f32_e32 v74, v74
	v_rcp_f32_e32 v75, v75
	v_rcp_f32_e32 v76, v76
	v_rcp_f32_e32 v77, v77
	s_mov_b64 s[6:7], 0x16000
	v_lshl_add_u64 v[244:245], v[244:245], 0, s[6:7]
	s_waitcnt lgkmcnt(0)
	global_store_dwordx4 v[244:245], v[94:97], off
	v_pk_mul_f32 v[70:71], v[70:71], v[78:79]
	v_pk_mul_f32 v[72:73], v[72:73], v[80:81]
	v_pk_mul_f32 v[66:67], v[66:67], v[74:75]
	v_pk_mul_f32 v[68:69], v[68:69], v[76:77]
	v_cvt_pk_bf16_f32 v70, v70, v71
	v_cvt_pk_bf16_f32 v71, v72, v73
	v_cvt_pk_bf16_f32 v72, v66, v67
	v_cvt_pk_bf16_f32 v73, v68, v69
	ds_write_b128 v146, v[70:73]
	ds_read_b128 v[78:81], v148
	v_cvt_f32_f16_sdwa v140, v143 dst_sel:DWORD dst_unused:UNUSED_PAD src0_sel:WORD_1
	v_pk_mul_f32 v[54:55], v[62:63], v[54:55]
	v_pk_mul_f32 v[56:57], v[64:65], v[56:57]
	v_pk_mul_f32 v[50:51], v[58:59], v[50:51]
	v_pk_mul_f32 v[52:53], v[60:61], v[52:53]
	v_mul_f32_e32 v142, 0xbfb8aa3b, v140
	v_mul_f32_e32 v144, v140, v140
	v_pk_mul_f32 v[62:63], v[62:63], v[142:143] op_sel_hi:[1,0]
	v_pk_mul_f32 v[64:65], v[64:65], v[142:143] op_sel_hi:[1,0]
	v_pk_mul_f32 v[58:59], v[58:59], v[142:143] op_sel_hi:[1,0]
	v_pk_mul_f32 v[60:61], v[60:61], v[142:143] op_sel_hi:[1,0]
	v_exp_f32_e32 v62, v62
	v_exp_f32_e32 v63, v63
	v_exp_f32_e32 v64, v64
	v_exp_f32_e32 v65, v65
	v_exp_f32_e32 v58, v58
	v_exp_f32_e32 v59, v59
	v_exp_f32_e32 v60, v60
	v_exp_f32_e32 v61, v61
	v_pk_mul_f32 v[54:55], v[54:55], v[144:145] op_sel_hi:[1,0]
	v_pk_mul_f32 v[56:57], v[56:57], v[144:145] op_sel_hi:[1,0]
	v_pk_mul_f32 v[50:51], v[50:51], v[144:145] op_sel_hi:[1,0]
	v_pk_mul_f32 v[52:53], v[52:53], v[144:145] op_sel_hi:[1,0]
	v_pk_add_f32 v[62:63], v[62:63], v[240:241]
	v_pk_add_f32 v[64:65], v[64:65], v[240:241]
	v_pk_add_f32 v[58:59], v[58:59], v[240:241]
	v_pk_add_f32 v[60:61], v[60:61], v[240:241]
	v_rcp_f32_e32 v62, v62
	v_rcp_f32_e32 v63, v63
	v_rcp_f32_e32 v64, v64
	v_rcp_f32_e32 v65, v65
	v_rcp_f32_e32 v58, v58
	v_rcp_f32_e32 v59, v59
	v_rcp_f32_e32 v60, v60
	v_rcp_f32_e32 v61, v61
	s_mov_b64 s[6:7], 0x16000
	v_lshl_add_u64 v[244:245], v[244:245], 0, s[6:7]
	s_waitcnt lgkmcnt(0)
; __device__ __forceinline__ unsigned cvt_pk_bf16(float lo, float hi) { f32x2_t v = {lo, hi}; bf16x2_t b = __builtin_convertvector(v, bf16x2_t); return __builtin_bit_cast(unsigned, b); }
; __device__ __forceinline__ float silu_mul(float a, float b) { return a * b * __builtin_amdgcn_rcpf(1.0f + __builtin_amdgcn_exp2f(a * -1.4426950408889634f)); }
;     __device__ __forceinline__ void operator()(const f32x4 (&acc)[2][2][4][2], const Unit& u, int wr, int wc, int fr, int fq, const float (&rr)[2][4]) const {
;     ...
;         for (int ai = 0; ai < 2; ++ai)
; #pragma unroll
;             for (int m = 0; m < 4; ++m) { const int row = row0 + ai * HALF + m * 16; const float r = rr[ai][m];
;                 const f32x4 g0 = acc[ai][0][m][0] * r, g1 = acc[ai][0][m][1] * r, u0 = acc[ai][1][m][0] * r, u1 = acc[ai][1][m][1] * r;
;                 u32x4 w; w.x = cvt_pk_bf16(silu_mul(g0[0], u0[0]), silu_mul(g0[1], u0[1])); w.y = cvt_pk_bf16(silu_mul(g0[2], u0[2]), silu_mul(g0[3], u0[3]));
;                 w.z = cvt_pk_bf16(silu_mul(g1[0], u1[0]), silu_mul(g1[1], u1[1])); w.w = cvt_pk_bf16(silu_mul(g1[2], u1[2]), silu_mul(g1[3], u1[3]));
;                 *(u32x4*)(O + (size_t)row * ldc + col0) = w; }
	global_store_dwordx4 v[244:245], v[78:81], off
	v_pk_mul_f32 v[54:55], v[54:55], v[62:63]
	v_pk_mul_f32 v[56:57], v[56:57], v[64:65]
	v_pk_mul_f32 v[50:51], v[50:51], v[58:59]
	v_pk_mul_f32 v[52:53], v[52:53], v[60:61]
	v_cvt_pk_bf16_f32 v54, v54, v55
	v_cvt_pk_bf16_f32 v55, v56, v57
	v_cvt_pk_bf16_f32 v56, v50, v51
	v_cvt_pk_bf16_f32 v57, v52, v53
	ds_write_b128 v146, v[54:57]
	ds_read_b128 v[62:65], v148
	v_cvt_f32_f16_sdwa v140, v145 dst_sel:DWORD dst_unused:UNUSED_PAD src0_sel:WORD_1
	v_pk_mul_f32 v[38:39], v[46:47], v[38:39]
	v_pk_mul_f32 v[40:41], v[48:49], v[40:41]
	v_pk_mul_f32 v[34:35], v[42:43], v[34:35]
	v_pk_mul_f32 v[36:37], v[44:45], v[36:37]
	v_mul_f32_e32 v142, 0xbfb8aa3b, v140
	v_mul_f32_e32 v144, v140, v140
	v_pk_mul_f32 v[46:47], v[46:47], v[142:143] op_sel_hi:[1,0]
	v_pk_mul_f32 v[48:49], v[48:49], v[142:143] op_sel_hi:[1,0]
	v_pk_mul_f32 v[42:43], v[42:43], v[142:143] op_sel_hi:[1,0]
	v_pk_mul_f32 v[44:45], v[44:45], v[142:143] op_sel_hi:[1,0]
	v_exp_f32_e32 v46, v46
	v_exp_f32_e32 v47, v47
	v_exp_f32_e32 v48, v48
	v_exp_f32_e32 v49, v49
	v_exp_f32_e32 v42, v42
	v_exp_f32_e32 v43, v43
	v_exp_f32_e32 v44, v44
	v_exp_f32_e32 v45, v45
	v_pk_mul_f32 v[38:39], v[38:39], v[144:145] op_sel_hi:[1,0]
	v_pk_mul_f32 v[40:41], v[40:41], v[144:145] op_sel_hi:[1,0]
	v_pk_mul_f32 v[34:35], v[34:35], v[144:145] op_sel_hi:[1,0]
	v_pk_mul_f32 v[36:37], v[36:37], v[144:145] op_sel_hi:[1,0]
	v_pk_add_f32 v[46:47], v[46:47], v[240:241]
	v_pk_add_f32 v[48:49], v[48:49], v[240:241]
	v_pk_add_f32 v[42:43], v[42:43], v[240:241]
	v_pk_add_f32 v[44:45], v[44:45], v[240:241]
	v_rcp_f32_e32 v46, v46
	v_rcp_f32_e32 v47, v47
	v_rcp_f32_e32 v48, v48
	v_rcp_f32_e32 v49, v49
	v_rcp_f32_e32 v42, v42
	v_rcp_f32_e32 v43, v43
	v_rcp_f32_e32 v44, v44
	v_rcp_f32_e32 v45, v45
	s_mov_b64 s[6:7], 0x6e000
	v_lshl_add_u64 v[244:245], v[244:245], 0, s[6:7]
	s_waitcnt lgkmcnt(0)
	global_store_dwordx4 v[244:245], v[62:65], off
	v_pk_mul_f32 v[38:39], v[38:39], v[46:47]
	v_pk_mul_f32 v[40:41], v[40:41], v[48:49]
	v_pk_mul_f32 v[34:35], v[34:35], v[42:43]
	v_pk_mul_f32 v[36:37], v[36:37], v[44:45]
	v_cvt_pk_bf16_f32 v38, v38, v39
	v_cvt_pk_bf16_f32 v39, v40, v41
	v_cvt_pk_bf16_f32 v40, v34, v35
	v_cvt_pk_bf16_f32 v41, v36, v37
	ds_write_b128 v146, v[38:41]
	ds_read_b128 v[46:49], v148
	v_cvt_f32_f16_sdwa v140, v147 dst_sel:DWORD dst_unused:UNUSED_PAD src0_sel:WORD_1
	v_pk_mul_f32 v[22:23], v[30:31], v[22:23]
	v_pk_mul_f32 v[24:25], v[32:33], v[24:25]
	v_pk_mul_f32 v[18:19], v[26:27], v[18:19]
	v_pk_mul_f32 v[20:21], v[28:29], v[20:21]
	v_mul_f32_e32 v142, 0xbfb8aa3b, v140
	v_mul_f32_e32 v144, v140, v140
	v_pk_mul_f32 v[30:31], v[30:31], v[142:143] op_sel_hi:[1,0]
	v_pk_mul_f32 v[32:33], v[32:33], v[142:143] op_sel_hi:[1,0]
	v_pk_mul_f32 v[26:27], v[26:27], v[142:143] op_sel_hi:[1,0]
	v_pk_mul_f32 v[28:29], v[28:29], v[142:143] op_sel_hi:[1,0]
	v_exp_f32_e32 v30, v30
	v_exp_f32_e32 v31, v31
	v_exp_f32_e32 v32, v32
	v_exp_f32_e32 v33, v33
	v_exp_f32_e32 v26, v26
	v_exp_f32_e32 v27, v27
	v_exp_f32_e32 v28, v28
	v_exp_f32_e32 v29, v29
	v_pk_mul_f32 v[22:23], v[22:23], v[144:145] op_sel_hi:[1,0]
	v_pk_mul_f32 v[24:25], v[24:25], v[144:145] op_sel_hi:[1,0]
	v_pk_mul_f32 v[18:19], v[18:19], v[144:145] op_sel_hi:[1,0]
	v_pk_mul_f32 v[20:21], v[20:21], v[144:145] op_sel_hi:[1,0]
	v_pk_add_f32 v[30:31], v[30:31], v[240:241]
	v_pk_add_f32 v[32:33], v[32:33], v[240:241]
	v_pk_add_f32 v[26:27], v[26:27], v[240:241]
	v_pk_add_f32 v[28:29], v[28:29], v[240:241]
	v_rcp_f32_e32 v30, v30
	v_rcp_f32_e32 v31, v31
	v_rcp_f32_e32 v32, v32
	v_rcp_f32_e32 v33, v33
	v_rcp_f32_e32 v26, v26
	v_rcp_f32_e32 v27, v27
	v_rcp_f32_e32 v28, v28
	v_rcp_f32_e32 v29, v29
	s_mov_b64 s[6:7], 0x16000
	v_lshl_add_u64 v[244:245], v[244:245], 0, s[6:7]
	s_waitcnt lgkmcnt(0)
	global_store_dwordx4 v[244:245], v[46:49], off
	v_pk_mul_f32 v[22:23], v[22:23], v[30:31]
	v_pk_mul_f32 v[24:25], v[24:25], v[32:33]
	v_pk_mul_f32 v[18:19], v[18:19], v[26:27]
	v_pk_mul_f32 v[20:21], v[20:21], v[28:29]
	v_cvt_pk_bf16_f32 v22, v22, v23
	v_cvt_pk_bf16_f32 v23, v24, v25
	v_cvt_pk_bf16_f32 v24, v18, v19
	v_cvt_pk_bf16_f32 v25, v20, v21
	ds_write_b128 v146, v[22:25]
	ds_read_b128 v[30:33], v148
	v_cvt_f32_f16_sdwa v140, v149 dst_sel:DWORD dst_unused:UNUSED_PAD src0_sel:WORD_1
	v_pk_mul_f32 v[6:7], v[14:15], v[6:7]
	v_pk_mul_f32 v[8:9], v[16:17], v[8:9]
	v_pk_mul_f32 v[2:3], v[10:11], v[2:3]
	v_pk_mul_f32 v[4:5], v[12:13], v[4:5]
	v_mul_f32_e32 v142, 0xbfb8aa3b, v140
	v_mul_f32_e32 v144, v140, v140
	v_pk_mul_f32 v[14:15], v[14:15], v[142:143] op_sel_hi:[1,0]
	v_pk_mul_f32 v[16:17], v[16:17], v[142:143] op_sel_hi:[1,0]
	v_pk_mul_f32 v[10:11], v[10:11], v[142:143] op_sel_hi:[1,0]
	v_pk_mul_f32 v[12:13], v[12:13], v[142:143] op_sel_hi:[1,0]
	v_exp_f32_e32 v14, v14
	v_exp_f32_e32 v15, v15
	v_exp_f32_e32 v16, v16
	v_exp_f32_e32 v17, v17
	v_exp_f32_e32 v10, v10
	v_exp_f32_e32 v11, v11
	v_exp_f32_e32 v12, v12
	v_exp_f32_e32 v13, v13
	v_pk_mul_f32 v[6:7], v[6:7], v[144:145] op_sel_hi:[1,0]
	v_pk_mul_f32 v[8:9], v[8:9], v[144:145] op_sel_hi:[1,0]
	v_pk_mul_f32 v[2:3], v[2:3], v[144:145] op_sel_hi:[1,0]
	v_pk_mul_f32 v[4:5], v[4:5], v[144:145] op_sel_hi:[1,0]
	v_pk_add_f32 v[14:15], v[14:15], v[240:241]
	v_pk_add_f32 v[16:17], v[16:17], v[240:241]
	v_pk_add_f32 v[10:11], v[10:11], v[240:241]
	v_pk_add_f32 v[12:13], v[12:13], v[240:241]
	v_rcp_f32_e32 v14, v14
	v_rcp_f32_e32 v15, v15
	v_rcp_f32_e32 v16, v16
	v_rcp_f32_e32 v17, v17
	v_rcp_f32_e32 v10, v10
	v_rcp_f32_e32 v11, v11
	v_rcp_f32_e32 v12, v12
	v_rcp_f32_e32 v13, v13
	s_mov_b64 s[6:7], 0x16000
	v_lshl_add_u64 v[244:245], v[244:245], 0, s[6:7]
	s_waitcnt lgkmcnt(0)
	global_store_dwordx4 v[244:245], v[30:33], off
	v_pk_mul_f32 v[6:7], v[6:7], v[14:15]
	v_pk_mul_f32 v[8:9], v[8:9], v[16:17]
	v_pk_mul_f32 v[2:3], v[2:3], v[10:11]
	v_pk_mul_f32 v[4:5], v[4:5], v[12:13]
	v_cvt_pk_bf16_f32 v6, v6, v7
	v_cvt_pk_bf16_f32 v7, v8, v9
	v_cvt_pk_bf16_f32 v8, v2, v3
	v_cvt_pk_bf16_f32 v9, v4, v5
	ds_write_b128 v146, v[6:9]
	ds_read_b128 v[14:17], v148
	s_mov_b64 s[6:7], 0x16000
	v_lshl_add_u64 v[244:245], v[244:245], 0, s[6:7]
	s_waitcnt lgkmcnt(0)
	global_store_dwordx4 v[244:245], v[14:17], off
	s_and_b64 vcc, exec, s[38:39]
	s_mov_b64 s[6:7], -1
	s_cbranch_vccnz .LBB0_604
	s_andn2_b64 vcc, exec, s[72:73]
	s_cbranch_vccnz .LBB0_603
	s_barrier
	s_branch .LBB0_603
